# EPD: P4/P6 epilogue row-sum-of-squares reduction - 32 ds_bpermute (xor 16/32) replaced by permlane16/32_swap + select
# speedup vs baseline: 1.0020x; 1.0020x over previous
; __device__ __forceinline__ u32x4 pack8(f32x4 a, f32x4 b) { u32x4 w; w.x = cvt_pk_bf16(a[0], a[1]); w.y = cvt_pk_bf16(a[2], a[3]); w.z = cvt_pk_bf16(b[0], b[1]); w.w = cvt_pk_bf16(b[2], b[3]); return w; }
;     __device__ __forceinline__ void operator()(const f32x4 (&acc)[2][2][4][2], const pg8::Unit& u, int wr, int wc, int fr, int fq) const {
; #pragma unroll
;         for (int ai = 0; ai < 2; ++ai)
; #pragma unroll
;             for (int m = 0; m < 4; ++m) { const int row = u.pm * 256 + ai * 128 + wr * 64 + m * 16 + fr; float ss = 0.f;
;                 const float* xrow = row < MP ? xp + (size_t)row * D : xs + (size_t)(row - MP) * D;
; #pragma unroll
;                 for (int bj = 0; bj < 2; ++bj) { const int col = u.pn * 256 + bj * 128 + wc * 32 + 8 * fq;
;                     f32x4 v0 = acc[ai][bj][m][0] + *(const f32x4*)(xrow + col), v1 = acc[ai][bj][m][1] + *(const f32x4*)(xrow + col + 4);
;                     ss += (v0[0] * v0[0] + v0[1] * v0[1]) + (v0[2] * v0[2] + v0[3] * v0[3]) + (v1[0] * v1[0] + v1[1] * v1[1]) + (v1[2] * v1[2] + v1[3] * v1[3]);
;                     *(u32x4*)(X2B + (size_t)row * D + col) = pack8(v0, v1); }
;                 ss += __shfl_xor(ss, 16); ss += __shfl_xor(ss, 32);
;                 if (fq == 0) atomicAdd(rss + row, ss); }
;     }
.LBB0_742:
	v_cmp_gt_u32_e64 s[56:57], 32, v160
	v_and_b32_e32 v253, 16, v160
	v_cmp_eq_u32_e64 s[58:59], 0, v253
	v_lshl_add_u32 v152, s24, 4, v133
	v_cmp_lt_i32_e32 vcc, s51, v152
	s_and_saveexec_b64 s[24:25], vcc
	s_xor_b64 s[24:25], exec, s[24:25]
	v_add_u32_e32 v140, 0xffffc000, v152
	v_lshlrev_b64 v[150:151], 12, v[140:141]
	v_lshl_add_u64 v[154:155], s[54:55], 0, v[150:151]
	v_mov_b32_e32 v153, v141
	s_andn2_saveexec_b64 s[24:25], s[24:25]
	v_ashrrev_i32_e32 v153, 31, v152
	v_lshlrev_b64 v[150:151], 12, v[152:153]
	v_lshl_add_u64 v[154:155], s[52:53], 0, v[150:151]
	s_or_b64 exec, exec, s[24:25]
	v_lshl_or_b32 v150, s22, 8, v156
	v_ashrrev_i32_e32 v151, 31, v150
	v_lshl_add_u64 v[154:155], v[150:151], 2, v[154:155]
	global_load_dwordx4 v[162:165], v[154:155], off
	global_load_dwordx4 v[166:169], v[154:155], off offset:16
	v_lshlrev_b64 v[170:171], 11, v[152:153]
	v_lshl_add_u64 v[170:171], s[6:7], 0, v[170:171]
	v_lshl_add_u64 v[170:171], v[150:151], 1, v[170:171]
	s_waitcnt vmcnt(0)
	v_pk_add_f32 v[126:127], v[126:127], v[164:165]
	v_pk_add_f32 v[172:173], v[124:125], v[162:163]
	v_pk_add_f32 v[168:169], v[122:123], v[168:169]
	v_pk_add_f32 v[166:167], v[120:121], v[166:167]
	v_cvt_pk_bf16_f32 v120, v172, v173
	v_cvt_pk_bf16_f32 v121, v126, v127
	v_mul_f32_e32 v140, v173, v173
	v_cvt_pk_bf16_f32 v122, v166, v167
	v_cvt_pk_bf16_f32 v123, v168, v169
	global_store_dwordx4 v[170:171], v[120:123], off
	global_load_dwordx4 v[122:125], v[154:155], off offset:512
	s_nop 0
	global_load_dwordx4 v[162:165], v[154:155], off offset:528
	v_mul_f32_e32 v127, v127, v127
	v_and_b32_e32 v121, 64, v160
	v_mul_f32_e32 v154, v167, v167
	v_fmac_f32_e32 v140, v172, v172
	v_fmac_f32_e32 v127, v126, v126
	v_xor_b32_e32 v120, 16, v160
	v_add_u32_e32 v121, 64, v121
	v_mul_f32_e32 v155, v169, v169
	v_fmac_f32_e32 v154, v166, v166
	v_add_f32_e32 v126, v140, v127
	v_cmp_lt_i32_e32 vcc, v120, v121
	v_fmac_f32_e32 v155, v168, v168
	v_add_f32_e32 v126, v126, v154
	v_cndmask_b32_e32 v120, v160, v120, vcc
	v_add_f32_e32 v126, v155, v126
	v_lshlrev_b32_e32 v120, 2, v120
	s_waitcnt vmcnt(1)
	v_pk_add_f32 v[118:119], v[118:119], v[124:125]
	v_pk_add_f32 v[116:117], v[116:117], v[122:123]
	s_waitcnt vmcnt(0)
	v_pk_add_f32 v[124:125], v[112:113], v[162:163]
	v_mul_f32_e32 v112, v117, v117
	v_mul_f32_e32 v113, v119, v119
	v_pk_add_f32 v[114:115], v[114:115], v[164:165]
	v_mul_f32_e32 v122, v125, v125
	v_fmac_f32_e32 v112, v116, v116
	v_fmac_f32_e32 v113, v118, v118
	v_mul_f32_e32 v123, v115, v115
	v_fmac_f32_e32 v122, v124, v124
	v_add_f32_e32 v112, v112, v113
	v_fmac_f32_e32 v123, v114, v114
	v_add_f32_e32 v112, v112, v122
	v_add_f32_e32 v112, v123, v112
	v_add_f32_e32 v112, v126, v112
	v_mov_b32_e32 v113, v112
	v_mov_b32_e32 v253, v112
	s_nop 1
	v_permlane16_swap_b32_e32 v113, v253
	v_cndmask_b32_e64 v113, v113, v253, s[58:59]
	v_xor_b32_e32 v122, 32, v160
	v_cmp_lt_i32_e32 vcc, v122, v121
	s_waitcnt lgkmcnt(0)
	v_add_f32_e32 v112, v112, v113
	v_cndmask_b32_e32 v121, v160, v122, vcc
	v_cvt_pk_bf16_f32 v122, v116, v117
	v_lshlrev_b32_e32 v116, 2, v121
	v_mov_b32_e32 v113, v112
	v_mov_b32_e32 v253, v112
	s_nop 1
	v_permlane32_swap_b32_e32 v113, v253
	v_cndmask_b32_e64 v113, v113, v253, s[56:57]
	v_cvt_pk_bf16_f32 v123, v118, v119
	v_cvt_pk_bf16_f32 v124, v124, v125
	v_cvt_pk_bf16_f32 v125, v114, v115
	global_store_dwordx4 v[170:171], v[122:125], off offset:256
	s_and_saveexec_b64 s[22:23], s[2:3]
	s_cbranch_execz .LBB0_748
	v_lshl_add_u64 v[114:115], v[152:153], 2, s[8:9]
	s_waitcnt lgkmcnt(0)
	v_add_f32_e32 v112, v112, v113
	global_atomic_add_f32 v[114:115], v112, off
.LBB0_748:
	s_or_b64 exec, exec, s[22:23]
	s_waitcnt lgkmcnt(0)
	v_add_u32_e32 v112, 16, v152
	v_cmp_lt_i32_e32 vcc, s51, v112
	s_and_saveexec_b64 s[22:23], vcc
	s_xor_b64 s[22:23], exec, s[22:23]
	v_add_u32_e32 v140, 0xffffc010, v152
	v_lshlrev_b64 v[114:115], 12, v[140:141]
	v_lshl_add_u64 v[114:115], s[54:55], 0, v[114:115]
	v_mov_b32_e32 v113, v141
	s_andn2_saveexec_b64 s[22:23], s[22:23]
	v_ashrrev_i32_e32 v113, 31, v112
	v_lshlrev_b64 v[114:115], 12, v[112:113]
	v_lshl_add_u64 v[114:115], s[52:53], 0, v[114:115]
	s_or_b64 exec, exec, s[22:23]
	v_lshl_add_u64 v[114:115], v[150:151], 2, v[114:115]
	global_load_dwordx4 v[122:125], v[114:115], off
	global_load_dwordx4 v[162:165], v[114:115], off offset:16
	v_lshlrev_b64 v[118:119], 11, v[112:113]
	v_lshl_add_u64 v[118:119], s[6:7], 0, v[118:119]
	v_lshl_add_u64 v[118:119], v[150:151], 1, v[118:119]
	s_waitcnt vmcnt(1)
	v_pk_add_f32 v[124:125], v[110:111], v[124:125]
	v_pk_add_f32 v[122:123], v[108:109], v[122:123]
	s_waitcnt vmcnt(0)
	v_pk_add_f32 v[126:127], v[106:107], v[164:165]
	v_pk_add_f32 v[154:155], v[104:105], v[162:163]
	v_cvt_pk_bf16_f32 v104, v122, v123
	v_cvt_pk_bf16_f32 v105, v124, v125
	v_mul_f32_e32 v121, v127, v127
	v_cvt_pk_bf16_f32 v106, v154, v155
	v_cvt_pk_bf16_f32 v107, v126, v127
	global_store_dwordx4 v[118:119], v[104:107], off
	global_load_dwordx4 v[104:107], v[114:115], off offset:512
	s_nop 0
	global_load_dwordx4 v[108:111], v[114:115], off offset:528
	v_mul_f32_e32 v114, v123, v123
	v_mul_f32_e32 v115, v125, v125
	v_mul_f32_e32 v117, v155, v155
	v_fmac_f32_e32 v114, v122, v122
	v_fmac_f32_e32 v115, v124, v124
	v_fmac_f32_e32 v117, v154, v154
	v_add_f32_e32 v114, v114, v115
	v_fmac_f32_e32 v121, v126, v126
	v_add_f32_e32 v114, v114, v117
	v_add_f32_e32 v114, v121, v114
	s_waitcnt vmcnt(1)
	v_pk_add_f32 v[102:103], v[102:103], v[106:107]
	v_pk_add_f32 v[100:101], v[100:101], v[104:105]
	s_waitcnt vmcnt(0)
	v_pk_add_f32 v[106:107], v[96:97], v[108:109]
	v_mul_f32_e32 v96, v101, v101
	v_mul_f32_e32 v97, v103, v103
	v_pk_add_f32 v[104:105], v[98:99], v[110:111]
	v_mul_f32_e32 v98, v107, v107
	v_fmac_f32_e32 v96, v100, v100
	v_fmac_f32_e32 v97, v102, v102
	v_mul_f32_e32 v99, v105, v105
	v_fmac_f32_e32 v98, v106, v106
	v_add_f32_e32 v96, v96, v97
	v_add_f32_e32 v96, v96, v98
	v_fmac_f32_e32 v99, v104, v104
	v_add_f32_e32 v96, v99, v96
	v_add_f32_e32 v96, v114, v96
	v_mov_b32_e32 v97, v96
	v_mov_b32_e32 v253, v96
	s_nop 1
	v_permlane16_swap_b32_e32 v97, v253
	v_cndmask_b32_e64 v97, v97, v253, s[58:59]
	v_cvt_pk_bf16_f32 v98, v100, v101
	v_cvt_pk_bf16_f32 v99, v102, v103
	v_cvt_pk_bf16_f32 v100, v106, v107
	v_cvt_pk_bf16_f32 v101, v104, v105
	s_waitcnt lgkmcnt(0)
	v_add_f32_e32 v96, v96, v97
	v_mov_b32_e32 v97, v96
	v_mov_b32_e32 v253, v96
	s_nop 1
	v_permlane32_swap_b32_e32 v97, v253
	v_cndmask_b32_e64 v97, v97, v253, s[56:57]
	global_store_dwordx4 v[118:119], v[98:101], off offset:256
	s_and_saveexec_b64 s[22:23], s[2:3]
	s_cbranch_execz .LBB0_754
	v_lshl_add_u64 v[98:99], v[112:113], 2, s[8:9]
	s_waitcnt lgkmcnt(0)
	v_add_f32_e32 v96, v96, v97
	global_atomic_add_f32 v[98:99], v96, off
; __device__ __forceinline__ u32x4 pack8(f32x4 a, f32x4 b) { u32x4 w; w.x = cvt_pk_bf16(a[0], a[1]); w.y = cvt_pk_bf16(a[2], a[3]); w.z = cvt_pk_bf16(b[0], b[1]); w.w = cvt_pk_bf16(b[2], b[3]); return w; }
;     __device__ __forceinline__ void operator()(const f32x4 (&acc)[2][2][4][2], const pg8::Unit& u, int wr, int wc, int fr, int fq) const {
;     ...
;             for (int m = 0; m < 4; ++m) { const int row = u.pm * 256 + ai * 128 + wr * 64 + m * 16 + fr; float ss = 0.f;
;                 const float* xrow = row < MP ? xp + (size_t)row * D : xs + (size_t)(row - MP) * D;
; #pragma unroll
;                 for (int bj = 0; bj < 2; ++bj) { const int col = u.pn * 256 + bj * 128 + wc * 32 + 8 * fq;
;                     f32x4 v0 = acc[ai][bj][m][0] + *(const f32x4*)(xrow + col), v1 = acc[ai][bj][m][1] + *(const f32x4*)(xrow + col + 4);
;                     ss += (v0[0] * v0[0] + v0[1] * v0[1]) + (v0[2] * v0[2] + v0[3] * v0[3]) + (v1[0] * v1[0] + v1[1] * v1[1]) + (v1[2] * v1[2] + v1[3] * v1[3]);
;                     *(u32x4*)(X2B + (size_t)row * D + col) = pack8(v0, v1); }
;                 ss += __shfl_xor(ss, 16); ss += __shfl_xor(ss, 32);
;                 if (fq == 0) atomicAdd(rss + row, ss); }
.LBB0_754:
	s_or_b64 exec, exec, s[22:23]
	s_waitcnt lgkmcnt(0)
	v_add_u32_e32 v96, 32, v152
	v_cmp_lt_i32_e32 vcc, s51, v96
	s_and_saveexec_b64 s[22:23], vcc
	s_xor_b64 s[22:23], exec, s[22:23]
	v_add_u32_e32 v140, 0xffffc020, v152
	v_lshlrev_b64 v[98:99], 12, v[140:141]
	v_lshl_add_u64 v[98:99], s[54:55], 0, v[98:99]
	v_mov_b32_e32 v97, v141
	s_andn2_saveexec_b64 s[22:23], s[22:23]
	v_ashrrev_i32_e32 v97, 31, v96
	v_lshlrev_b64 v[98:99], 12, v[96:97]
	v_lshl_add_u64 v[98:99], s[52:53], 0, v[98:99]
	s_or_b64 exec, exec, s[22:23]
	v_lshl_add_u64 v[106:107], v[150:151], 2, v[98:99]
	global_load_dwordx4 v[98:101], v[106:107], off
	global_load_dwordx4 v[102:105], v[106:107], off offset:16
	v_lshlrev_b64 v[108:109], 11, v[96:97]
	v_lshl_add_u64 v[108:109], s[6:7], 0, v[108:109]
	v_lshl_add_u64 v[108:109], v[150:151], 1, v[108:109]
	s_waitcnt vmcnt(1)
	v_pk_add_f32 v[100:101], v[94:95], v[100:101]
	v_pk_add_f32 v[98:99], v[92:93], v[98:99]
	s_waitcnt vmcnt(0)
	v_pk_add_f32 v[104:105], v[90:91], v[104:105]
	v_pk_add_f32 v[102:103], v[88:89], v[102:103]
	v_cvt_pk_bf16_f32 v88, v98, v99
	v_cvt_pk_bf16_f32 v89, v100, v101
	v_mul_f32_e32 v99, v99, v99
	v_cvt_pk_bf16_f32 v90, v102, v103
	v_cvt_pk_bf16_f32 v91, v104, v105
	global_store_dwordx4 v[108:109], v[88:91], off
	global_load_dwordx4 v[88:91], v[106:107], off offset:512
	s_nop 0
	global_load_dwordx4 v[92:95], v[106:107], off offset:528
	v_mul_f32_e32 v101, v101, v101
	v_mul_f32_e32 v103, v103, v103
	v_fmac_f32_e32 v99, v98, v98
	v_fmac_f32_e32 v101, v100, v100
	v_mul_f32_e32 v105, v105, v105
	v_fmac_f32_e32 v103, v102, v102
	v_add_f32_e32 v98, v99, v101
	v_fmac_f32_e32 v105, v104, v104
	v_add_f32_e32 v98, v98, v103
	v_add_f32_e32 v98, v105, v98
	s_waitcnt vmcnt(1)
	v_pk_add_f32 v[86:87], v[86:87], v[90:91]
	v_pk_add_f32 v[84:85], v[84:85], v[88:89]
	s_waitcnt vmcnt(0)
	v_pk_add_f32 v[90:91], v[80:81], v[92:93]
	v_mul_f32_e32 v80, v85, v85
	v_mul_f32_e32 v81, v87, v87
	v_pk_add_f32 v[88:89], v[82:83], v[94:95]
	v_mul_f32_e32 v82, v91, v91
	v_fmac_f32_e32 v80, v84, v84
	v_fmac_f32_e32 v81, v86, v86
	v_mul_f32_e32 v83, v89, v89
	v_fmac_f32_e32 v82, v90, v90
	v_add_f32_e32 v80, v80, v81
	v_add_f32_e32 v80, v80, v82
	v_fmac_f32_e32 v83, v88, v88
	v_add_f32_e32 v80, v83, v80
	v_add_f32_e32 v80, v98, v80
	v_mov_b32_e32 v81, v80
	v_mov_b32_e32 v253, v80
	s_nop 1
	v_permlane16_swap_b32_e32 v81, v253
	v_cndmask_b32_e64 v81, v81, v253, s[58:59]
	v_cvt_pk_bf16_f32 v82, v84, v85
	v_cvt_pk_bf16_f32 v83, v86, v87
	v_cvt_pk_bf16_f32 v84, v90, v91
	v_cvt_pk_bf16_f32 v85, v88, v89
	s_waitcnt lgkmcnt(0)
	v_add_f32_e32 v80, v80, v81
	v_mov_b32_e32 v81, v80
	v_mov_b32_e32 v253, v80
	s_nop 1
	v_permlane32_swap_b32_e32 v81, v253
	v_cndmask_b32_e64 v81, v81, v253, s[56:57]
	global_store_dwordx4 v[108:109], v[82:85], off offset:256
	s_and_saveexec_b64 s[22:23], s[2:3]
	s_cbranch_execz .LBB0_760
	v_lshl_add_u64 v[82:83], v[96:97], 2, s[8:9]
	s_waitcnt lgkmcnt(0)
	v_add_f32_e32 v80, v80, v81
	global_atomic_add_f32 v[82:83], v80, off
.LBB0_760:
	s_or_b64 exec, exec, s[22:23]
	s_waitcnt lgkmcnt(0)
	v_add_u32_e32 v80, 48, v152
	v_cmp_lt_i32_e32 vcc, s51, v80
	s_and_saveexec_b64 s[22:23], vcc
	s_xor_b64 s[22:23], exec, s[22:23]
	v_add_u32_e32 v140, 0xffffc030, v152
	v_lshlrev_b64 v[82:83], 12, v[140:141]
	v_lshl_add_u64 v[82:83], s[54:55], 0, v[82:83]
	v_mov_b32_e32 v81, v141
	s_andn2_saveexec_b64 s[22:23], s[22:23]
	v_ashrrev_i32_e32 v81, 31, v80
	v_lshlrev_b64 v[82:83], 12, v[80:81]
	v_lshl_add_u64 v[82:83], s[52:53], 0, v[82:83]
	s_or_b64 exec, exec, s[22:23]
	v_lshl_add_u64 v[90:91], v[150:151], 2, v[82:83]
	global_load_dwordx4 v[82:85], v[90:91], off
	global_load_dwordx4 v[86:89], v[90:91], off offset:16
	v_lshlrev_b64 v[92:93], 11, v[80:81]
	v_lshl_add_u64 v[92:93], s[6:7], 0, v[92:93]
	v_lshl_add_u64 v[92:93], v[150:151], 1, v[92:93]
	s_waitcnt vmcnt(1)
	v_pk_add_f32 v[84:85], v[78:79], v[84:85]
	v_pk_add_f32 v[82:83], v[76:77], v[82:83]
	s_waitcnt vmcnt(0)
	v_pk_add_f32 v[88:89], v[74:75], v[88:89]
	v_pk_add_f32 v[86:87], v[72:73], v[86:87]
	v_cvt_pk_bf16_f32 v72, v82, v83
	v_cvt_pk_bf16_f32 v73, v84, v85
	v_mul_f32_e32 v83, v83, v83
	v_cvt_pk_bf16_f32 v74, v86, v87
	v_cvt_pk_bf16_f32 v75, v88, v89
	global_store_dwordx4 v[92:93], v[72:75], off
	global_load_dwordx4 v[72:75], v[90:91], off offset:512
	s_nop 0
	global_load_dwordx4 v[76:79], v[90:91], off offset:528
	v_mul_f32_e32 v85, v85, v85
	v_mul_f32_e32 v87, v87, v87
	v_fmac_f32_e32 v83, v82, v82
	v_fmac_f32_e32 v85, v84, v84
	v_mul_f32_e32 v89, v89, v89
	v_fmac_f32_e32 v87, v86, v86
	v_add_f32_e32 v82, v83, v85
	v_fmac_f32_e32 v89, v88, v88
	v_add_f32_e32 v82, v82, v87
	v_add_f32_e32 v82, v89, v82
	s_waitcnt vmcnt(1)
	v_pk_add_f32 v[70:71], v[70:71], v[74:75]
	v_pk_add_f32 v[68:69], v[68:69], v[72:73]
	s_waitcnt vmcnt(0)
	v_pk_add_f32 v[74:75], v[64:65], v[76:77]
	v_mul_f32_e32 v64, v69, v69
	v_mul_f32_e32 v65, v71, v71
	v_pk_add_f32 v[72:73], v[66:67], v[78:79]
	v_mul_f32_e32 v66, v75, v75
	v_fmac_f32_e32 v64, v68, v68
	v_fmac_f32_e32 v65, v70, v70
	v_mul_f32_e32 v67, v73, v73
	v_fmac_f32_e32 v66, v74, v74
	v_add_f32_e32 v64, v64, v65
	v_add_f32_e32 v64, v64, v66
	v_fmac_f32_e32 v67, v72, v72
	v_add_f32_e32 v64, v67, v64
	v_add_f32_e32 v64, v82, v64
	v_mov_b32_e32 v65, v64
	v_mov_b32_e32 v253, v64
	s_nop 1
	v_permlane16_swap_b32_e32 v65, v253
	v_cndmask_b32_e64 v65, v65, v253, s[58:59]
	v_cvt_pk_bf16_f32 v66, v68, v69
	v_cvt_pk_bf16_f32 v67, v70, v71
	v_cvt_pk_bf16_f32 v68, v74, v75
	v_cvt_pk_bf16_f32 v69, v72, v73
	s_waitcnt lgkmcnt(0)
	v_add_f32_e32 v64, v64, v65
	v_mov_b32_e32 v65, v64
	v_mov_b32_e32 v253, v64
	s_nop 1
	v_permlane32_swap_b32_e32 v65, v253
	v_cndmask_b32_e64 v65, v65, v253, s[56:57]
	global_store_dwordx4 v[92:93], v[66:69], off offset:256
	s_and_saveexec_b64 s[22:23], s[2:3]
	s_cbranch_execz .LBB0_766
	v_lshl_add_u64 v[66:67], v[80:81], 2, s[8:9]
	s_waitcnt lgkmcnt(0)
	v_add_f32_e32 v64, v64, v65
	global_atomic_add_f32 v[66:67], v64, off
; __device__ __forceinline__ u32x4 pack8(f32x4 a, f32x4 b) { u32x4 w; w.x = cvt_pk_bf16(a[0], a[1]); w.y = cvt_pk_bf16(a[2], a[3]); w.z = cvt_pk_bf16(b[0], b[1]); w.w = cvt_pk_bf16(b[2], b[3]); return w; }
;     __device__ __forceinline__ void operator()(const f32x4 (&acc)[2][2][4][2], const pg8::Unit& u, int wr, int wc, int fr, int fq) const {
;     ...
;             for (int m = 0; m < 4; ++m) { const int row = u.pm * 256 + ai * 128 + wr * 64 + m * 16 + fr; float ss = 0.f;
;                 const float* xrow = row < MP ? xp + (size_t)row * D : xs + (size_t)(row - MP) * D;
; #pragma unroll
;                 for (int bj = 0; bj < 2; ++bj) { const int col = u.pn * 256 + bj * 128 + wc * 32 + 8 * fq;
;                     f32x4 v0 = acc[ai][bj][m][0] + *(const f32x4*)(xrow + col), v1 = acc[ai][bj][m][1] + *(const f32x4*)(xrow + col + 4);
;                     ss += (v0[0] * v0[0] + v0[1] * v0[1]) + (v0[2] * v0[2] + v0[3] * v0[3]) + (v1[0] * v1[0] + v1[1] * v1[1]) + (v1[2] * v1[2] + v1[3] * v1[3]);
;                     *(u32x4*)(X2B + (size_t)row * D + col) = pack8(v0, v1); }
;                 ss += __shfl_xor(ss, 16); ss += __shfl_xor(ss, 32);
;                 if (fq == 0) atomicAdd(rss + row, ss); }
.LBB0_766:
	s_or_b64 exec, exec, s[22:23]
	s_waitcnt lgkmcnt(0)
	v_add_u32_e32 v64, 0x80, v152
	v_cmp_lt_i32_e32 vcc, s51, v64
	s_and_saveexec_b64 s[22:23], vcc
	s_xor_b64 s[22:23], exec, s[22:23]
	v_add_u32_e32 v140, 0xffffc080, v152
	v_lshlrev_b64 v[66:67], 12, v[140:141]
	v_lshl_add_u64 v[66:67], s[54:55], 0, v[66:67]
	v_mov_b32_e32 v65, v141
	s_andn2_saveexec_b64 s[22:23], s[22:23]
	v_ashrrev_i32_e32 v65, 31, v64
	v_lshlrev_b64 v[66:67], 12, v[64:65]
	v_lshl_add_u64 v[66:67], s[52:53], 0, v[66:67]
	s_or_b64 exec, exec, s[22:23]
	v_lshl_add_u64 v[74:75], v[150:151], 2, v[66:67]
	global_load_dwordx4 v[66:69], v[74:75], off
	global_load_dwordx4 v[70:73], v[74:75], off offset:16
	v_lshlrev_b64 v[76:77], 11, v[64:65]
	v_lshl_add_u64 v[76:77], s[6:7], 0, v[76:77]
	v_lshl_add_u64 v[76:77], v[150:151], 1, v[76:77]
	s_waitcnt vmcnt(1)
	v_pk_add_f32 v[68:69], v[62:63], v[68:69]
	v_pk_add_f32 v[66:67], v[60:61], v[66:67]
	s_waitcnt vmcnt(0)
	v_pk_add_f32 v[72:73], v[58:59], v[72:73]
	v_pk_add_f32 v[70:71], v[56:57], v[70:71]
	v_cvt_pk_bf16_f32 v56, v66, v67
	v_cvt_pk_bf16_f32 v57, v68, v69
	v_mul_f32_e32 v67, v67, v67
	v_cvt_pk_bf16_f32 v58, v70, v71
	v_cvt_pk_bf16_f32 v59, v72, v73
	global_store_dwordx4 v[76:77], v[56:59], off
	global_load_dwordx4 v[56:59], v[74:75], off offset:512
	s_nop 0
	global_load_dwordx4 v[60:63], v[74:75], off offset:528
	v_mul_f32_e32 v69, v69, v69
	v_mul_f32_e32 v71, v71, v71
	v_fmac_f32_e32 v67, v66, v66
	v_fmac_f32_e32 v69, v68, v68
	v_mul_f32_e32 v73, v73, v73
	v_fmac_f32_e32 v71, v70, v70
	v_add_f32_e32 v66, v67, v69
	v_fmac_f32_e32 v73, v72, v72
	v_add_f32_e32 v66, v66, v71
	v_add_f32_e32 v66, v73, v66
	s_waitcnt vmcnt(1)
	v_pk_add_f32 v[54:55], v[54:55], v[58:59]
	v_pk_add_f32 v[52:53], v[52:53], v[56:57]
	s_waitcnt vmcnt(0)
	v_pk_add_f32 v[58:59], v[48:49], v[60:61]
	v_mul_f32_e32 v48, v53, v53
	v_mul_f32_e32 v49, v55, v55
	v_pk_add_f32 v[56:57], v[50:51], v[62:63]
	v_mul_f32_e32 v50, v59, v59
	v_fmac_f32_e32 v48, v52, v52
	v_fmac_f32_e32 v49, v54, v54
	v_mul_f32_e32 v51, v57, v57
	v_fmac_f32_e32 v50, v58, v58
	v_add_f32_e32 v48, v48, v49
	v_add_f32_e32 v48, v48, v50
	v_fmac_f32_e32 v51, v56, v56
	v_add_f32_e32 v48, v51, v48
	v_add_f32_e32 v48, v66, v48
	v_mov_b32_e32 v49, v48
	v_mov_b32_e32 v253, v48
	s_nop 1
	v_permlane16_swap_b32_e32 v49, v253
	v_cndmask_b32_e64 v49, v49, v253, s[58:59]
	v_cvt_pk_bf16_f32 v50, v52, v53
	v_cvt_pk_bf16_f32 v51, v54, v55
	v_cvt_pk_bf16_f32 v52, v58, v59
	v_cvt_pk_bf16_f32 v53, v56, v57
	s_waitcnt lgkmcnt(0)
	v_add_f32_e32 v48, v48, v49
	v_mov_b32_e32 v49, v48
	v_mov_b32_e32 v253, v48
	s_nop 1
	v_permlane32_swap_b32_e32 v49, v253
	v_cndmask_b32_e64 v49, v49, v253, s[56:57]
	global_store_dwordx4 v[76:77], v[50:53], off offset:256
	s_and_saveexec_b64 s[22:23], s[2:3]
	s_cbranch_execz .LBB0_772
	v_lshl_add_u64 v[50:51], v[64:65], 2, s[8:9]
	s_waitcnt lgkmcnt(0)
	v_add_f32_e32 v48, v48, v49
	global_atomic_add_f32 v[50:51], v48, off
.LBB0_772:
	s_or_b64 exec, exec, s[22:23]
	s_waitcnt lgkmcnt(0)
	v_add_u32_e32 v48, 0x90, v152
	v_cmp_lt_i32_e32 vcc, s51, v48
	s_and_saveexec_b64 s[22:23], vcc
	s_xor_b64 s[22:23], exec, s[22:23]
	v_add_u32_e32 v140, 0xffffc090, v152
	v_lshlrev_b64 v[50:51], 12, v[140:141]
	v_lshl_add_u64 v[50:51], s[54:55], 0, v[50:51]
	v_mov_b32_e32 v49, v141
	s_andn2_saveexec_b64 s[22:23], s[22:23]
	v_ashrrev_i32_e32 v49, 31, v48
	v_lshlrev_b64 v[50:51], 12, v[48:49]
	v_lshl_add_u64 v[50:51], s[52:53], 0, v[50:51]
	s_or_b64 exec, exec, s[22:23]
	v_lshl_add_u64 v[58:59], v[150:151], 2, v[50:51]
	global_load_dwordx4 v[50:53], v[58:59], off
	global_load_dwordx4 v[54:57], v[58:59], off offset:16
	v_lshlrev_b64 v[60:61], 11, v[48:49]
	v_lshl_add_u64 v[60:61], s[6:7], 0, v[60:61]
	v_lshl_add_u64 v[60:61], v[150:151], 1, v[60:61]
	s_waitcnt vmcnt(1)
	v_pk_add_f32 v[52:53], v[46:47], v[52:53]
	v_pk_add_f32 v[50:51], v[44:45], v[50:51]
	s_waitcnt vmcnt(0)
	v_pk_add_f32 v[56:57], v[42:43], v[56:57]
	v_pk_add_f32 v[54:55], v[40:41], v[54:55]
	v_cvt_pk_bf16_f32 v40, v50, v51
	v_cvt_pk_bf16_f32 v41, v52, v53
	v_mul_f32_e32 v51, v51, v51
	v_cvt_pk_bf16_f32 v42, v54, v55
	v_cvt_pk_bf16_f32 v43, v56, v57
	global_store_dwordx4 v[60:61], v[40:43], off
	global_load_dwordx4 v[40:43], v[58:59], off offset:512
	s_nop 0
	global_load_dwordx4 v[44:47], v[58:59], off offset:528
	v_mul_f32_e32 v53, v53, v53
	v_mul_f32_e32 v55, v55, v55
	v_fmac_f32_e32 v51, v50, v50
	v_fmac_f32_e32 v53, v52, v52
	v_mul_f32_e32 v57, v57, v57
	v_fmac_f32_e32 v55, v54, v54
	v_add_f32_e32 v50, v51, v53
	v_fmac_f32_e32 v57, v56, v56
	v_add_f32_e32 v50, v50, v55
	v_add_f32_e32 v50, v57, v50
	s_waitcnt vmcnt(1)
	v_pk_add_f32 v[38:39], v[38:39], v[42:43]
	v_pk_add_f32 v[36:37], v[36:37], v[40:41]
	s_waitcnt vmcnt(0)
	v_pk_add_f32 v[42:43], v[32:33], v[44:45]
	v_mul_f32_e32 v32, v37, v37
	v_mul_f32_e32 v33, v39, v39
	v_pk_add_f32 v[40:41], v[34:35], v[46:47]
	v_mul_f32_e32 v34, v43, v43
	v_fmac_f32_e32 v32, v36, v36
	v_fmac_f32_e32 v33, v38, v38
	v_mul_f32_e32 v35, v41, v41
	v_fmac_f32_e32 v34, v42, v42
	v_add_f32_e32 v32, v32, v33
	v_add_f32_e32 v32, v32, v34
	v_fmac_f32_e32 v35, v40, v40
	v_add_f32_e32 v32, v35, v32
	v_add_f32_e32 v32, v50, v32
	v_mov_b32_e32 v33, v32
	v_mov_b32_e32 v253, v32
	s_nop 1
	v_permlane16_swap_b32_e32 v33, v253
	v_cndmask_b32_e64 v33, v33, v253, s[58:59]
	v_cvt_pk_bf16_f32 v34, v36, v37
	v_cvt_pk_bf16_f32 v35, v38, v39
	v_cvt_pk_bf16_f32 v36, v42, v43
	v_cvt_pk_bf16_f32 v37, v40, v41
	s_waitcnt lgkmcnt(0)
	v_add_f32_e32 v32, v32, v33
	v_mov_b32_e32 v33, v32
	v_mov_b32_e32 v253, v32
	s_nop 1
	v_permlane32_swap_b32_e32 v33, v253
	v_cndmask_b32_e64 v33, v33, v253, s[56:57]
	global_store_dwordx4 v[60:61], v[34:37], off offset:256
	s_and_saveexec_b64 s[22:23], s[2:3]
	s_cbranch_execz .LBB0_778
	v_lshl_add_u64 v[34:35], v[48:49], 2, s[8:9]
	s_waitcnt lgkmcnt(0)
	v_add_f32_e32 v32, v32, v33
	global_atomic_add_f32 v[34:35], v32, off
; __device__ __forceinline__ u32x4 pack8(f32x4 a, f32x4 b) { u32x4 w; w.x = cvt_pk_bf16(a[0], a[1]); w.y = cvt_pk_bf16(a[2], a[3]); w.z = cvt_pk_bf16(b[0], b[1]); w.w = cvt_pk_bf16(b[2], b[3]); return w; }
;     __device__ __forceinline__ void operator()(const f32x4 (&acc)[2][2][4][2], const pg8::Unit& u, int wr, int wc, int fr, int fq) const {
;     ...
;             for (int m = 0; m < 4; ++m) { const int row = u.pm * 256 + ai * 128 + wr * 64 + m * 16 + fr; float ss = 0.f;
;                 const float* xrow = row < MP ? xp + (size_t)row * D : xs + (size_t)(row - MP) * D;
; #pragma unroll
;                 for (int bj = 0; bj < 2; ++bj) { const int col = u.pn * 256 + bj * 128 + wc * 32 + 8 * fq;
;                     f32x4 v0 = acc[ai][bj][m][0] + *(const f32x4*)(xrow + col), v1 = acc[ai][bj][m][1] + *(const f32x4*)(xrow + col + 4);
;                     ss += (v0[0] * v0[0] + v0[1] * v0[1]) + (v0[2] * v0[2] + v0[3] * v0[3]) + (v1[0] * v1[0] + v1[1] * v1[1]) + (v1[2] * v1[2] + v1[3] * v1[3]);
;                     *(u32x4*)(X2B + (size_t)row * D + col) = pack8(v0, v1); }
;                 ss += __shfl_xor(ss, 16); ss += __shfl_xor(ss, 32);
;                 if (fq == 0) atomicAdd(rss + row, ss); }
.LBB0_778:
	s_or_b64 exec, exec, s[22:23]
	s_waitcnt lgkmcnt(0)
	v_add_u32_e32 v32, 0xa0, v152
	v_cmp_lt_i32_e32 vcc, s51, v32
	s_and_saveexec_b64 s[22:23], vcc
	s_xor_b64 s[22:23], exec, s[22:23]
	v_add_u32_e32 v140, 0xffffc0a0, v152
	v_lshlrev_b64 v[34:35], 12, v[140:141]
	v_lshl_add_u64 v[34:35], s[54:55], 0, v[34:35]
	v_mov_b32_e32 v33, v141
	s_andn2_saveexec_b64 s[22:23], s[22:23]
	v_ashrrev_i32_e32 v33, 31, v32
	v_lshlrev_b64 v[34:35], 12, v[32:33]
	v_lshl_add_u64 v[34:35], s[52:53], 0, v[34:35]
	s_or_b64 exec, exec, s[22:23]
	v_lshl_add_u64 v[42:43], v[150:151], 2, v[34:35]
	global_load_dwordx4 v[34:37], v[42:43], off
	global_load_dwordx4 v[38:41], v[42:43], off offset:16
	v_lshlrev_b64 v[44:45], 11, v[32:33]
	v_lshl_add_u64 v[44:45], s[6:7], 0, v[44:45]
	v_lshl_add_u64 v[44:45], v[150:151], 1, v[44:45]
	s_waitcnt vmcnt(1)
	v_pk_add_f32 v[36:37], v[30:31], v[36:37]
	v_pk_add_f32 v[34:35], v[28:29], v[34:35]
	s_waitcnt vmcnt(0)
	v_pk_add_f32 v[40:41], v[26:27], v[40:41]
	v_pk_add_f32 v[38:39], v[24:25], v[38:39]
	v_cvt_pk_bf16_f32 v24, v34, v35
	v_cvt_pk_bf16_f32 v25, v36, v37
	v_mul_f32_e32 v35, v35, v35
	v_cvt_pk_bf16_f32 v26, v38, v39
	v_cvt_pk_bf16_f32 v27, v40, v41
	global_store_dwordx4 v[44:45], v[24:27], off
	global_load_dwordx4 v[24:27], v[42:43], off offset:512
	s_nop 0
	global_load_dwordx4 v[28:31], v[42:43], off offset:528
	v_mul_f32_e32 v37, v37, v37
	v_mul_f32_e32 v39, v39, v39
	v_fmac_f32_e32 v35, v34, v34
	v_fmac_f32_e32 v37, v36, v36
	v_mul_f32_e32 v41, v41, v41
	v_fmac_f32_e32 v39, v38, v38
	v_add_f32_e32 v34, v35, v37
	v_fmac_f32_e32 v41, v40, v40
	v_add_f32_e32 v34, v34, v39
	v_add_f32_e32 v34, v41, v34
	s_waitcnt vmcnt(1)
	v_pk_add_f32 v[22:23], v[22:23], v[26:27]
	v_pk_add_f32 v[20:21], v[20:21], v[24:25]
	s_waitcnt vmcnt(0)
	v_pk_add_f32 v[26:27], v[16:17], v[28:29]
	v_mul_f32_e32 v16, v21, v21
	v_mul_f32_e32 v17, v23, v23
	v_pk_add_f32 v[24:25], v[18:19], v[30:31]
	v_mul_f32_e32 v18, v27, v27
	v_fmac_f32_e32 v16, v20, v20
	v_fmac_f32_e32 v17, v22, v22
	v_mul_f32_e32 v19, v25, v25
	v_fmac_f32_e32 v18, v26, v26
	v_add_f32_e32 v16, v16, v17
	v_add_f32_e32 v16, v16, v18
	v_fmac_f32_e32 v19, v24, v24
	v_add_f32_e32 v16, v19, v16
	v_add_f32_e32 v16, v34, v16
	v_mov_b32_e32 v17, v16
	v_mov_b32_e32 v253, v16
	s_nop 1
	v_permlane16_swap_b32_e32 v17, v253
	v_cndmask_b32_e64 v17, v17, v253, s[58:59]
	v_cvt_pk_bf16_f32 v18, v20, v21
	v_cvt_pk_bf16_f32 v19, v22, v23
	v_cvt_pk_bf16_f32 v20, v26, v27
	v_cvt_pk_bf16_f32 v21, v24, v25
	s_waitcnt lgkmcnt(0)
	v_add_f32_e32 v16, v16, v17
	v_mov_b32_e32 v17, v16
	v_mov_b32_e32 v253, v16
	s_nop 1
	v_permlane32_swap_b32_e32 v17, v253
	v_cndmask_b32_e64 v17, v17, v253, s[56:57]
	global_store_dwordx4 v[44:45], v[18:21], off offset:256
	s_and_saveexec_b64 s[22:23], s[2:3]
	s_cbranch_execz .LBB0_784
	v_lshl_add_u64 v[18:19], v[32:33], 2, s[8:9]
	s_waitcnt lgkmcnt(0)
	v_add_f32_e32 v16, v16, v17
	global_atomic_add_f32 v[18:19], v16, off
.LBB0_784:
	s_or_b64 exec, exec, s[22:23]
	s_waitcnt lgkmcnt(0)
	v_add_u32_e32 v16, 0xb0, v152
	v_cmp_lt_i32_e32 vcc, s51, v16
	s_and_saveexec_b64 s[22:23], vcc
	s_xor_b64 s[22:23], exec, s[22:23]
	v_add_u32_e32 v140, 0xffffc0b0, v152
	v_lshlrev_b64 v[18:19], 12, v[140:141]
	v_lshl_add_u64 v[18:19], s[54:55], 0, v[18:19]
	v_mov_b32_e32 v17, v141
	s_andn2_saveexec_b64 s[22:23], s[22:23]
	v_ashrrev_i32_e32 v17, 31, v16
	v_lshlrev_b64 v[18:19], 12, v[16:17]
	v_lshl_add_u64 v[18:19], s[52:53], 0, v[18:19]
	s_or_b64 exec, exec, s[22:23]
	v_lshl_add_u64 v[26:27], v[150:151], 2, v[18:19]
	global_load_dwordx4 v[18:21], v[26:27], off
	global_load_dwordx4 v[22:25], v[26:27], off offset:16
	v_lshlrev_b64 v[28:29], 11, v[16:17]
	v_lshl_add_u64 v[28:29], s[6:7], 0, v[28:29]
	v_lshl_add_u64 v[28:29], v[150:151], 1, v[28:29]
	s_waitcnt vmcnt(1)
	v_pk_add_f32 v[20:21], v[14:15], v[20:21]
	v_pk_add_f32 v[18:19], v[12:13], v[18:19]
	s_waitcnt vmcnt(0)
	v_pk_add_f32 v[24:25], v[10:11], v[24:25]
	v_pk_add_f32 v[22:23], v[8:9], v[22:23]
	v_cvt_pk_bf16_f32 v8, v18, v19
	v_cvt_pk_bf16_f32 v9, v20, v21
	v_mul_f32_e32 v19, v19, v19
	v_cvt_pk_bf16_f32 v10, v22, v23
	v_cvt_pk_bf16_f32 v11, v24, v25
	global_store_dwordx4 v[28:29], v[8:11], off
	global_load_dwordx4 v[8:11], v[26:27], off offset:512
	s_nop 0
	global_load_dwordx4 v[12:15], v[26:27], off offset:528
	v_mul_f32_e32 v21, v21, v21
	v_mul_f32_e32 v23, v23, v23
	v_fmac_f32_e32 v19, v18, v18
	v_fmac_f32_e32 v21, v20, v20
	v_mul_f32_e32 v25, v25, v25
	v_fmac_f32_e32 v23, v22, v22
	v_add_f32_e32 v18, v19, v21
	v_fmac_f32_e32 v25, v24, v24
	v_add_f32_e32 v18, v18, v23
	v_add_f32_e32 v18, v25, v18
	s_waitcnt vmcnt(1)
	v_pk_add_f32 v[6:7], v[6:7], v[10:11]
	v_pk_add_f32 v[4:5], v[4:5], v[8:9]
	s_waitcnt vmcnt(0)
	v_pk_add_f32 v[10:11], v[0:1], v[12:13]
	v_mul_f32_e32 v0, v5, v5
	v_mul_f32_e32 v1, v7, v7
	v_pk_add_f32 v[8:9], v[2:3], v[14:15]
	v_mul_f32_e32 v2, v11, v11
	v_fmac_f32_e32 v0, v4, v4
	v_fmac_f32_e32 v1, v6, v6
	v_mul_f32_e32 v3, v9, v9
	v_fmac_f32_e32 v2, v10, v10
	v_add_f32_e32 v0, v0, v1
	v_add_f32_e32 v0, v0, v2
	v_fmac_f32_e32 v3, v8, v8
	v_add_f32_e32 v0, v3, v0
	v_add_f32_e32 v0, v18, v0
	v_mov_b32_e32 v1, v0
	v_mov_b32_e32 v253, v0
	s_nop 1
	v_permlane16_swap_b32_e32 v1, v253
	v_cndmask_b32_e64 v1, v1, v253, s[58:59]
	v_cvt_pk_bf16_f32 v2, v4, v5
	v_cvt_pk_bf16_f32 v3, v6, v7
	v_cvt_pk_bf16_f32 v4, v10, v11
	v_cvt_pk_bf16_f32 v5, v8, v9
	s_waitcnt lgkmcnt(0)
	v_add_f32_e32 v0, v0, v1
	v_mov_b32_e32 v1, v0
	v_mov_b32_e32 v253, v0
	s_nop 1
	v_permlane32_swap_b32_e32 v1, v253
	v_cndmask_b32_e64 v1, v1, v253, s[56:57]
	global_store_dwordx4 v[28:29], v[2:5], off offset:256
	s_and_saveexec_b64 s[22:23], s[2:3]
	s_cbranch_execz .LBB0_790
	v_lshl_add_u64 v[2:3], v[16:17], 2, s[8:9]
	s_waitcnt lgkmcnt(0)
	v_add_f32_e32 v0, v0, v1
	global_atomic_add_f32 v[2:3], v0, off

; __device__ __forceinline__ u32x4 pack8(f32x4 a, f32x4 b) { u32x4 w; w.x = cvt_pk_bf16(a[0], a[1]); w.y = cvt_pk_bf16(a[2], a[3]); w.z = cvt_pk_bf16(b[0], b[1]); w.w = cvt_pk_bf16(b[2], b[3]); return w; }
;     __device__ __forceinline__ void operator()(const f32x4 (&acc)[2][2][4][2], const pg8::Unit& u, int wr, int wc, int fr, int fq) const {
;     ...
;             for (int m = 0; m < 4; ++m) { const int row = u.pm * 256 + ai * 128 + wr * 64 + m * 16 + fr; float ss = 0.f;
; #pragma unroll
;                 for (int bj = 0; bj < 2; ++bj) { const int col = u.pn * 256 + bj * 128 + wc * 32 + 8 * fq;
;                     f32x4 x0, x1; unpack_bf16x8(*(const u32x4*)(X2B + (size_t)row * D + col), x0, x1);
;                     const f32x4 v0 = acc[ai][bj][m][0] + x0, v1 = acc[ai][bj][m][1] + x1;
;                     ss += (v0[0] * v0[0] + v0[1] * v0[1]) + (v0[2] * v0[2] + v0[3] * v0[3]) + (v1[0] * v1[0] + v1[1] * v1[1]) + (v1[2] * v1[2] + v1[3] * v1[3]);
;                     *(u32x4*)(X3B + (size_t)row * D + col) = pack8(v0, v1); }
;                 ss += __shfl_xor(ss, 16); ss += __shfl_xor(ss, 32);
;                 if (fq == 0) atomicAdd(rss + row, ss); }
.LBB0_934:
	v_cmp_gt_u32_e64 s[56:57], 32, v155
	v_and_b32_e32 v253, 16, v155
	v_cmp_eq_u32_e64 s[58:59], 0, v253
	v_lshl_add_u32 v148, s48, 4, v133
	v_lshl_or_b32 v146, s47, 8, v151
	v_ashrrev_i32_e32 v149, 31, v148
	v_lshlrev_b64 v[160:161], 11, v[148:149]
	v_ashrrev_i32_e32 v147, 31, v146
	v_lshl_add_u64 v[156:157], s[8:9], 0, v[160:161]
	v_lshlrev_b64 v[146:147], 1, v[146:147]
	v_lshl_add_u64 v[162:163], v[156:157], 0, v[146:147]
	v_mov_b64_e32 v[242:243], v[162:163]
	s_mov_b64 s[96:97], 0x8000
	s_mov_b64 s[98:99], 0x28000
	global_load_dwordx4 v[170:173], v[242:243], off
	global_load_dwordx4 v[174:177], v[242:243], off offset:256
	v_lshl_add_u64 v[242:243], v[242:243], 0, s[96:97]
	global_load_dwordx4 v[178:181], v[242:243], off
	global_load_dwordx4 v[182:185], v[242:243], off offset:256
	v_lshl_add_u64 v[242:243], v[242:243], 0, s[96:97]
	global_load_dwordx4 v[186:189], v[242:243], off
	global_load_dwordx4 v[190:193], v[242:243], off offset:256
	v_lshl_add_u64 v[242:243], v[242:243], 0, s[96:97]
	global_load_dwordx4 v[194:197], v[242:243], off
	global_load_dwordx4 v[198:201], v[242:243], off offset:256
	v_lshl_add_u64 v[242:243], v[242:243], 0, s[98:99]
	global_load_dwordx4 v[202:205], v[242:243], off
	global_load_dwordx4 v[206:209], v[242:243], off offset:256
	v_lshl_add_u64 v[242:243], v[242:243], 0, s[96:97]
	global_load_dwordx4 v[210:213], v[242:243], off
	global_load_dwordx4 v[214:217], v[242:243], off offset:256
	v_lshl_add_u64 v[242:243], v[242:243], 0, s[96:97]
	global_load_dwordx4 v[218:221], v[242:243], off
	global_load_dwordx4 v[222:225], v[242:243], off offset:256
	v_lshl_add_u64 v[242:243], v[242:243], 0, s[96:97]
	global_load_dwordx4 v[234:237], v[242:243], off
	global_load_dwordx4 v[238:241], v[242:243], off offset:256
	s_waitcnt vmcnt(15)
	v_lshlrev_b32_e32 v164, 16, v170
	v_and_b32_e32 v165, 0xffff0000, v170
	v_lshlrev_b32_e32 v156, 16, v171
	v_and_b32_e32 v157, 0xffff0000, v171
	v_lshlrev_b32_e32 v166, 16, v172
	v_and_b32_e32 v167, 0xffff0000, v172
	v_lshlrev_b32_e32 v158, 16, v173
	v_and_b32_e32 v159, 0xffff0000, v173
	v_pk_add_f32 v[126:127], v[126:127], v[156:157]
	v_pk_add_f32 v[164:165], v[124:125], v[164:165]
	v_pk_add_f32 v[168:169], v[122:123], v[158:159]
	v_pk_add_f32 v[166:167], v[120:121], v[166:167]
	v_cvt_pk_bf16_f32 v122, v164, v165
	v_cvt_pk_bf16_f32 v123, v126, v127
	v_and_b32_e32 v121, 64, v155
	v_cvt_pk_bf16_f32 v124, v166, v167
	v_cvt_pk_bf16_f32 v125, v168, v169
	s_nop 0
	v_xor_b32_e32 v120, 16, v155
	v_add_u32_e32 v121, 64, v121
	v_xor_b32_e32 v162, 32, v155
	v_cmp_lt_i32_e32 vcc, v120, v121
	v_mul_f32_e32 v127, v127, v127
	v_mul_f32_e32 v163, v167, v167
	v_cndmask_b32_e32 v120, v155, v120, vcc
	v_cmp_lt_i32_e32 vcc, v162, v121
	v_fmac_f32_e32 v127, v126, v126
	v_fmac_f32_e32 v163, v166, v166
	v_cndmask_b32_e32 v121, v155, v162, vcc
	v_mul_f32_e32 v162, v165, v165
	v_fmac_f32_e32 v162, v164, v164
	v_mul_f32_e32 v165, v169, v169
	v_add_f32_e32 v126, v162, v127
	v_fmac_f32_e32 v165, v168, v168
	v_add_f32_e32 v126, v163, v126
	v_add_f32_e32 v164, v165, v126
	v_lshlrev_b32_e32 v120, 2, v120
	s_waitcnt vmcnt(14)
	v_lshlrev_b32_e32 v126, 16, v174
	v_and_b32_e32 v127, 0xffff0000, v174
	v_lshlrev_b32_e32 v156, 16, v175
	v_and_b32_e32 v157, 0xffff0000, v175
	v_lshlrev_b32_e32 v162, 16, v176
	v_and_b32_e32 v163, 0xffff0000, v176
	v_pk_add_f32 v[118:119], v[118:119], v[156:157]
	v_pk_add_f32 v[116:117], v[116:117], v[126:127]
	v_lshlrev_b32_e32 v158, 16, v177
	v_and_b32_e32 v159, 0xffff0000, v177
	v_pk_add_f32 v[156:157], v[112:113], v[162:163]
	v_mul_f32_e32 v112, v117, v117
	v_mul_f32_e32 v113, v119, v119
	v_pk_add_f32 v[126:127], v[114:115], v[158:159]
	v_mul_f32_e32 v114, v157, v157
	v_fmac_f32_e32 v112, v116, v116
	v_fmac_f32_e32 v113, v118, v118
	v_mul_f32_e32 v115, v127, v127
	v_fmac_f32_e32 v114, v156, v156
	v_add_f32_e32 v112, v112, v113
	v_fmac_f32_e32 v115, v126, v126
	v_add_f32_e32 v112, v114, v112
	v_add_f32_e32 v112, v115, v112
	v_add_f32_e32 v114, v164, v112
	v_mov_b32_e32 v115, v114
	v_mov_b32_e32 v253, v114
	s_nop 1
	v_permlane16_swap_b32_e32 v115, v253
	v_cndmask_b32_e64 v115, v115, v253, s[58:59]
	v_lshl_add_u64 v[112:113], s[10:11], 0, v[160:161]
	v_lshl_add_u64 v[158:159], v[112:113], 0, v[146:147]
	global_store_dwordx4 v[158:159], v[122:125], off
	v_cvt_pk_bf16_f32 v116, v116, v117
	s_waitcnt lgkmcnt(0)
	v_add_f32_e32 v112, v114, v115
	v_lshlrev_b32_e32 v114, 2, v121
	v_mov_b32_e32 v113, v112
	v_mov_b32_e32 v253, v112
	s_nop 1
	v_permlane32_swap_b32_e32 v113, v253
	v_cndmask_b32_e64 v113, v113, v253, s[56:57]
	v_cvt_pk_bf16_f32 v117, v118, v119
	v_cvt_pk_bf16_f32 v118, v156, v157
	v_cvt_pk_bf16_f32 v119, v126, v127
	global_store_dwordx4 v[158:159], v[116:119], off offset:256
	s_and_saveexec_b64 s[20:21], s[2:3]
	s_cbranch_execz .LBB0_936
	v_lshl_add_u64 v[116:117], v[148:149], 2, s[12:13]
	s_waitcnt lgkmcnt(0)
	v_add_f32_e32 v112, v112, v113
	global_atomic_add_f32 v[116:117], v112, off
; __device__ __forceinline__ u32x4 pack8(f32x4 a, f32x4 b) { u32x4 w; w.x = cvt_pk_bf16(a[0], a[1]); w.y = cvt_pk_bf16(a[2], a[3]); w.z = cvt_pk_bf16(b[0], b[1]); w.w = cvt_pk_bf16(b[2], b[3]); return w; }
;     __device__ __forceinline__ void operator()(const f32x4 (&acc)[2][2][4][2], const pg8::Unit& u, int wr, int wc, int fr, int fq) const {
;     ...
;             for (int m = 0; m < 4; ++m) { const int row = u.pm * 256 + ai * 128 + wr * 64 + m * 16 + fr; float ss = 0.f;
; #pragma unroll
;                 for (int bj = 0; bj < 2; ++bj) { const int col = u.pn * 256 + bj * 128 + wc * 32 + 8 * fq;
;                     f32x4 x0, x1; unpack_bf16x8(*(const u32x4*)(X2B + (size_t)row * D + col), x0, x1);
;                     const f32x4 v0 = acc[ai][bj][m][0] + x0, v1 = acc[ai][bj][m][1] + x1;
;                     ss += (v0[0] * v0[0] + v0[1] * v0[1]) + (v0[2] * v0[2] + v0[3] * v0[3]) + (v1[0] * v1[0] + v1[1] * v1[1]) + (v1[2] * v1[2] + v1[3] * v1[3]);
;                     *(u32x4*)(X3B + (size_t)row * D + col) = pack8(v0, v1); }
;                 ss += __shfl_xor(ss, 16); ss += __shfl_xor(ss, 32);
;                 if (fq == 0) atomicAdd(rss + row, ss); }
.LBB0_936:
	s_or_b64 exec, exec, s[20:21]
	v_add_u32_e32 v112, 16, v148
	s_waitcnt lgkmcnt(0)
	v_ashrrev_i32_e32 v113, 31, v112
	v_lshlrev_b64 v[122:123], 11, v[112:113]
	v_lshl_add_u64 v[116:117], s[8:9], 0, v[122:123]
	v_lshl_add_u64 v[124:125], v[116:117], 0, v[146:147]
	s_nop 0
	s_waitcnt vmcnt(15)
	v_lshlrev_b32_e32 v126, 16, v178
	v_and_b32_e32 v127, 0xffff0000, v178
	v_lshlrev_b32_e32 v116, 16, v179
	v_and_b32_e32 v117, 0xffff0000, v179
	v_lshlrev_b32_e32 v156, 16, v180
	v_and_b32_e32 v157, 0xffff0000, v180
	v_lshlrev_b32_e32 v118, 16, v181
	v_and_b32_e32 v119, 0xffff0000, v181
	v_pk_add_f32 v[116:117], v[110:111], v[116:117]
	v_pk_add_f32 v[126:127], v[108:109], v[126:127]
	v_pk_add_f32 v[118:119], v[106:107], v[118:119]
	v_pk_add_f32 v[156:157], v[104:105], v[156:157]
	v_cvt_pk_bf16_f32 v104, v126, v127
	v_cvt_pk_bf16_f32 v105, v116, v117
	v_mul_f32_e32 v115, v127, v127
	v_cvt_pk_bf16_f32 v106, v156, v157
	v_cvt_pk_bf16_f32 v107, v118, v119
	s_nop 0
	v_mul_f32_e32 v117, v117, v117
	v_mul_f32_e32 v121, v157, v157
	v_fmac_f32_e32 v115, v126, v126
	v_fmac_f32_e32 v117, v116, v116
	v_mul_f32_e32 v119, v119, v119
	v_fmac_f32_e32 v121, v156, v156
	v_add_f32_e32 v115, v115, v117
	v_fmac_f32_e32 v119, v118, v118
	v_add_f32_e32 v115, v121, v115
	v_add_f32_e32 v115, v119, v115
	s_waitcnt vmcnt(14)
	v_lshlrev_b32_e32 v116, 16, v182
	v_and_b32_e32 v117, 0xffff0000, v182
	v_lshlrev_b32_e32 v108, 16, v183
	v_and_b32_e32 v109, 0xffff0000, v183
	v_lshlrev_b32_e32 v118, 16, v184
	v_and_b32_e32 v119, 0xffff0000, v184
	v_lshlrev_b32_e32 v110, 16, v185
	v_and_b32_e32 v111, 0xffff0000, v185
	v_pk_add_f32 v[102:103], v[102:103], v[108:109]
	v_pk_add_f32 v[100:101], v[100:101], v[116:117]
	v_pk_add_f32 v[108:109], v[98:99], v[110:111]
	v_pk_add_f32 v[110:111], v[96:97], v[118:119]
	v_mul_f32_e32 v96, v101, v101
	v_mul_f32_e32 v97, v103, v103
	v_mul_f32_e32 v98, v111, v111
	v_fmac_f32_e32 v96, v100, v100
	v_fmac_f32_e32 v97, v102, v102
	v_mul_f32_e32 v99, v109, v109
	v_fmac_f32_e32 v98, v110, v110
	v_add_f32_e32 v96, v96, v97
	v_add_f32_e32 v96, v98, v96
	v_fmac_f32_e32 v99, v108, v108
	v_add_f32_e32 v96, v99, v96
	v_add_f32_e32 v99, v115, v96
	v_mov_b32_e32 v115, v99
	v_mov_b32_e32 v253, v99
	s_nop 1
	v_permlane16_swap_b32_e32 v115, v253
	v_cndmask_b32_e64 v115, v115, v253, s[58:59]
	v_lshl_add_u64 v[96:97], s[10:11], 0, v[122:123]
	v_lshl_add_u64 v[116:117], v[96:97], 0, v[146:147]
	global_store_dwordx4 v[116:117], v[104:107], off
	v_cvt_pk_bf16_f32 v98, v100, v101
	s_waitcnt lgkmcnt(0)
	v_add_f32_e32 v96, v99, v115
	v_mov_b32_e32 v97, v96
	v_mov_b32_e32 v253, v96
	s_nop 1
	v_permlane32_swap_b32_e32 v97, v253
	v_cndmask_b32_e64 v97, v97, v253, s[56:57]
	v_cvt_pk_bf16_f32 v99, v102, v103
	v_cvt_pk_bf16_f32 v100, v110, v111
	v_cvt_pk_bf16_f32 v101, v108, v109
	global_store_dwordx4 v[116:117], v[98:101], off offset:256
	s_and_saveexec_b64 s[20:21], s[2:3]
	s_cbranch_execz .LBB0_938
	v_lshl_add_u64 v[98:99], v[112:113], 2, s[12:13]
	s_waitcnt lgkmcnt(0)
	v_add_f32_e32 v96, v96, v97
	global_atomic_add_f32 v[98:99], v96, off
.LBB0_938:
	s_or_b64 exec, exec, s[20:21]
	v_add_u32_e32 v96, 32, v148
	s_waitcnt lgkmcnt(0)
	v_ashrrev_i32_e32 v97, 31, v96
	v_lshlrev_b64 v[102:103], 11, v[96:97]
	v_lshl_add_u64 v[98:99], s[8:9], 0, v[102:103]
	v_lshl_add_u64 v[104:105], v[98:99], 0, v[146:147]
	s_nop 0
	s_waitcnt vmcnt(15)
	v_lshlrev_b32_e32 v106, 16, v186
	v_and_b32_e32 v107, 0xffff0000, v186
	v_lshlrev_b32_e32 v98, 16, v187
	v_and_b32_e32 v99, 0xffff0000, v187
	v_lshlrev_b32_e32 v108, 16, v188
	v_and_b32_e32 v109, 0xffff0000, v188
	v_lshlrev_b32_e32 v100, 16, v189
	v_and_b32_e32 v101, 0xffff0000, v189
	v_pk_add_f32 v[98:99], v[94:95], v[98:99]
	v_pk_add_f32 v[106:107], v[92:93], v[106:107]
	v_pk_add_f32 v[100:101], v[90:91], v[100:101]
	v_pk_add_f32 v[108:109], v[88:89], v[108:109]
	v_cvt_pk_bf16_f32 v88, v106, v107
	v_cvt_pk_bf16_f32 v89, v98, v99
	v_mul_f32_e32 v99, v99, v99
	v_cvt_pk_bf16_f32 v90, v108, v109
	v_cvt_pk_bf16_f32 v91, v100, v101
	s_nop 0
	v_mul_f32_e32 v104, v107, v107
	v_mul_f32_e32 v105, v109, v109
	v_fmac_f32_e32 v104, v106, v106
	v_fmac_f32_e32 v99, v98, v98
	v_mul_f32_e32 v101, v101, v101
	v_fmac_f32_e32 v105, v108, v108
	v_add_f32_e32 v98, v104, v99
	v_fmac_f32_e32 v101, v100, v100
	v_add_f32_e32 v98, v105, v98
	v_add_f32_e32 v104, v101, v98
	s_waitcnt vmcnt(14)
	v_lshlrev_b32_e32 v98, 16, v190
	v_and_b32_e32 v99, 0xffff0000, v190
	v_lshlrev_b32_e32 v92, 16, v191
	v_and_b32_e32 v93, 0xffff0000, v191
	v_lshlrev_b32_e32 v100, 16, v192
	v_and_b32_e32 v101, 0xffff0000, v192
	v_lshlrev_b32_e32 v94, 16, v193
	v_and_b32_e32 v95, 0xffff0000, v193
	v_pk_add_f32 v[86:87], v[86:87], v[92:93]
	v_pk_add_f32 v[84:85], v[84:85], v[98:99]
	v_pk_add_f32 v[92:93], v[82:83], v[94:95]
	v_pk_add_f32 v[94:95], v[80:81], v[100:101]
	v_mul_f32_e32 v80, v85, v85
	v_mul_f32_e32 v81, v87, v87
	v_mul_f32_e32 v82, v95, v95
	v_fmac_f32_e32 v80, v84, v84
	v_fmac_f32_e32 v81, v86, v86
	v_mul_f32_e32 v83, v93, v93
	v_fmac_f32_e32 v82, v94, v94
	v_add_f32_e32 v80, v80, v81
	v_add_f32_e32 v80, v82, v80
	v_fmac_f32_e32 v83, v92, v92
	v_add_f32_e32 v80, v83, v80
	v_add_f32_e32 v83, v104, v80
	v_mov_b32_e32 v100, v83
	v_mov_b32_e32 v253, v83
	s_nop 1
	v_permlane16_swap_b32_e32 v100, v253
	v_cndmask_b32_e64 v100, v100, v253, s[58:59]
	v_lshl_add_u64 v[80:81], s[10:11], 0, v[102:103]
	v_lshl_add_u64 v[98:99], v[80:81], 0, v[146:147]
	global_store_dwordx4 v[98:99], v[88:91], off
	v_cvt_pk_bf16_f32 v82, v84, v85
	s_waitcnt lgkmcnt(0)
	v_add_f32_e32 v80, v83, v100
	v_mov_b32_e32 v81, v80
	v_mov_b32_e32 v253, v80
	s_nop 1
	v_permlane32_swap_b32_e32 v81, v253
	v_cndmask_b32_e64 v81, v81, v253, s[56:57]
	v_cvt_pk_bf16_f32 v83, v86, v87
	v_cvt_pk_bf16_f32 v84, v94, v95
	v_cvt_pk_bf16_f32 v85, v92, v93
	global_store_dwordx4 v[98:99], v[82:85], off offset:256
	s_and_saveexec_b64 s[20:21], s[2:3]
	s_cbranch_execz .LBB0_940
	v_lshl_add_u64 v[82:83], v[96:97], 2, s[12:13]
	s_waitcnt lgkmcnt(0)
	v_add_f32_e32 v80, v80, v81
	global_atomic_add_f32 v[82:83], v80, off
; __device__ __forceinline__ u32x4 pack8(f32x4 a, f32x4 b) { u32x4 w; w.x = cvt_pk_bf16(a[0], a[1]); w.y = cvt_pk_bf16(a[2], a[3]); w.z = cvt_pk_bf16(b[0], b[1]); w.w = cvt_pk_bf16(b[2], b[3]); return w; }
;     __device__ __forceinline__ void operator()(const f32x4 (&acc)[2][2][4][2], const pg8::Unit& u, int wr, int wc, int fr, int fq) const {
;     ...
;             for (int m = 0; m < 4; ++m) { const int row = u.pm * 256 + ai * 128 + wr * 64 + m * 16 + fr; float ss = 0.f;
; #pragma unroll
;                 for (int bj = 0; bj < 2; ++bj) { const int col = u.pn * 256 + bj * 128 + wc * 32 + 8 * fq;
;                     f32x4 x0, x1; unpack_bf16x8(*(const u32x4*)(X2B + (size_t)row * D + col), x0, x1);
;                     const f32x4 v0 = acc[ai][bj][m][0] + x0, v1 = acc[ai][bj][m][1] + x1;
;                     ss += (v0[0] * v0[0] + v0[1] * v0[1]) + (v0[2] * v0[2] + v0[3] * v0[3]) + (v1[0] * v1[0] + v1[1] * v1[1]) + (v1[2] * v1[2] + v1[3] * v1[3]);
;                     *(u32x4*)(X3B + (size_t)row * D + col) = pack8(v0, v1); }
;                 ss += __shfl_xor(ss, 16); ss += __shfl_xor(ss, 32);
;                 if (fq == 0) atomicAdd(rss + row, ss); }
.LBB0_940:
	s_or_b64 exec, exec, s[20:21]
	v_add_u32_e32 v80, 48, v148
	s_waitcnt lgkmcnt(0)
	v_ashrrev_i32_e32 v81, 31, v80
	v_lshlrev_b64 v[86:87], 11, v[80:81]
	v_lshl_add_u64 v[82:83], s[8:9], 0, v[86:87]
	v_lshl_add_u64 v[88:89], v[82:83], 0, v[146:147]
	s_nop 0
	s_waitcnt vmcnt(15)
	v_lshlrev_b32_e32 v90, 16, v194
	v_and_b32_e32 v91, 0xffff0000, v194
	v_lshlrev_b32_e32 v82, 16, v195
	v_and_b32_e32 v83, 0xffff0000, v195
	v_lshlrev_b32_e32 v92, 16, v196
	v_and_b32_e32 v93, 0xffff0000, v196
	v_lshlrev_b32_e32 v84, 16, v197
	v_and_b32_e32 v85, 0xffff0000, v197
	v_pk_add_f32 v[82:83], v[78:79], v[82:83]
	v_pk_add_f32 v[90:91], v[76:77], v[90:91]
	v_pk_add_f32 v[84:85], v[74:75], v[84:85]
	v_pk_add_f32 v[92:93], v[72:73], v[92:93]
	v_cvt_pk_bf16_f32 v72, v90, v91
	v_cvt_pk_bf16_f32 v73, v82, v83
	v_mul_f32_e32 v83, v83, v83
	v_cvt_pk_bf16_f32 v74, v92, v93
	v_cvt_pk_bf16_f32 v75, v84, v85
	s_nop 0
	v_mul_f32_e32 v88, v91, v91
	v_mul_f32_e32 v89, v93, v93
	v_fmac_f32_e32 v88, v90, v90
	v_fmac_f32_e32 v83, v82, v82
	v_mul_f32_e32 v85, v85, v85
	v_fmac_f32_e32 v89, v92, v92
	v_add_f32_e32 v82, v88, v83
	v_fmac_f32_e32 v85, v84, v84
	v_add_f32_e32 v82, v89, v82
	v_add_f32_e32 v88, v85, v82
	s_waitcnt vmcnt(14)
	v_lshlrev_b32_e32 v82, 16, v198
	v_and_b32_e32 v83, 0xffff0000, v198
	v_lshlrev_b32_e32 v76, 16, v199
	v_and_b32_e32 v77, 0xffff0000, v199
	v_lshlrev_b32_e32 v84, 16, v200
	v_and_b32_e32 v85, 0xffff0000, v200
	v_lshlrev_b32_e32 v78, 16, v201
	v_and_b32_e32 v79, 0xffff0000, v201
	v_pk_add_f32 v[70:71], v[70:71], v[76:77]
	v_pk_add_f32 v[68:69], v[68:69], v[82:83]
	v_pk_add_f32 v[76:77], v[66:67], v[78:79]
	v_pk_add_f32 v[78:79], v[64:65], v[84:85]
	v_mul_f32_e32 v64, v69, v69
	v_mul_f32_e32 v65, v71, v71
	v_mul_f32_e32 v66, v79, v79
	v_fmac_f32_e32 v64, v68, v68
	v_fmac_f32_e32 v65, v70, v70
	v_mul_f32_e32 v67, v77, v77
	v_fmac_f32_e32 v66, v78, v78
	v_add_f32_e32 v64, v64, v65
	v_add_f32_e32 v64, v66, v64
	v_fmac_f32_e32 v67, v76, v76
	v_add_f32_e32 v64, v67, v64
	v_add_f32_e32 v67, v88, v64
	v_mov_b32_e32 v84, v67
	v_mov_b32_e32 v253, v67
	s_nop 1
	v_permlane16_swap_b32_e32 v84, v253
	v_cndmask_b32_e64 v84, v84, v253, s[58:59]
	v_lshl_add_u64 v[64:65], s[10:11], 0, v[86:87]
	v_lshl_add_u64 v[82:83], v[64:65], 0, v[146:147]
	global_store_dwordx4 v[82:83], v[72:75], off
	v_cvt_pk_bf16_f32 v66, v68, v69
	s_waitcnt lgkmcnt(0)
	v_add_f32_e32 v64, v67, v84
	v_mov_b32_e32 v65, v64
	v_mov_b32_e32 v253, v64
	s_nop 1
	v_permlane32_swap_b32_e32 v65, v253
	v_cndmask_b32_e64 v65, v65, v253, s[56:57]
	v_cvt_pk_bf16_f32 v67, v70, v71
	v_cvt_pk_bf16_f32 v68, v78, v79
	v_cvt_pk_bf16_f32 v69, v76, v77
	global_store_dwordx4 v[82:83], v[66:69], off offset:256
	s_and_saveexec_b64 s[20:21], s[2:3]
	s_cbranch_execz .LBB0_942
	v_lshl_add_u64 v[66:67], v[80:81], 2, s[12:13]
	s_waitcnt lgkmcnt(0)
	v_add_f32_e32 v64, v64, v65
	global_atomic_add_f32 v[66:67], v64, off
.LBB0_942:
	s_or_b64 exec, exec, s[20:21]
	v_add_u32_e32 v64, 0x80, v148
	s_waitcnt lgkmcnt(0)
	v_ashrrev_i32_e32 v65, 31, v64
	v_lshlrev_b64 v[70:71], 11, v[64:65]
	v_lshl_add_u64 v[66:67], s[8:9], 0, v[70:71]
	v_lshl_add_u64 v[72:73], v[66:67], 0, v[146:147]
	s_nop 0
	s_waitcnt vmcnt(15)
	v_lshlrev_b32_e32 v74, 16, v202
	v_and_b32_e32 v75, 0xffff0000, v202
	v_lshlrev_b32_e32 v66, 16, v203
	v_and_b32_e32 v67, 0xffff0000, v203
	v_lshlrev_b32_e32 v76, 16, v204
	v_and_b32_e32 v77, 0xffff0000, v204
	v_lshlrev_b32_e32 v68, 16, v205
	v_and_b32_e32 v69, 0xffff0000, v205
	v_pk_add_f32 v[66:67], v[62:63], v[66:67]
	v_pk_add_f32 v[74:75], v[60:61], v[74:75]
	v_pk_add_f32 v[68:69], v[58:59], v[68:69]
	v_pk_add_f32 v[76:77], v[56:57], v[76:77]
	v_cvt_pk_bf16_f32 v56, v74, v75
	v_cvt_pk_bf16_f32 v57, v66, v67
	v_mul_f32_e32 v67, v67, v67
	v_cvt_pk_bf16_f32 v58, v76, v77
	v_cvt_pk_bf16_f32 v59, v68, v69
	s_nop 0
	v_mul_f32_e32 v72, v75, v75
	v_mul_f32_e32 v73, v77, v77
	v_fmac_f32_e32 v72, v74, v74
	v_fmac_f32_e32 v67, v66, v66
	v_mul_f32_e32 v69, v69, v69
	v_fmac_f32_e32 v73, v76, v76
	v_add_f32_e32 v66, v72, v67
	v_fmac_f32_e32 v69, v68, v68
	v_add_f32_e32 v66, v73, v66
	v_add_f32_e32 v72, v69, v66
	s_waitcnt vmcnt(14)
	v_lshlrev_b32_e32 v66, 16, v206
	v_and_b32_e32 v67, 0xffff0000, v206
	v_lshlrev_b32_e32 v60, 16, v207
	v_and_b32_e32 v61, 0xffff0000, v207
	v_lshlrev_b32_e32 v68, 16, v208
	v_and_b32_e32 v69, 0xffff0000, v208
	v_lshlrev_b32_e32 v62, 16, v209
	v_and_b32_e32 v63, 0xffff0000, v209
	v_pk_add_f32 v[54:55], v[54:55], v[60:61]
	v_pk_add_f32 v[52:53], v[52:53], v[66:67]
	v_pk_add_f32 v[60:61], v[50:51], v[62:63]
	v_pk_add_f32 v[62:63], v[48:49], v[68:69]
	v_mul_f32_e32 v48, v53, v53
	v_mul_f32_e32 v49, v55, v55
	v_mul_f32_e32 v50, v63, v63
	v_fmac_f32_e32 v48, v52, v52
	v_fmac_f32_e32 v49, v54, v54
	v_mul_f32_e32 v51, v61, v61
	v_fmac_f32_e32 v50, v62, v62
	v_add_f32_e32 v48, v48, v49
	v_add_f32_e32 v48, v50, v48
	v_fmac_f32_e32 v51, v60, v60
	v_add_f32_e32 v48, v51, v48
	v_add_f32_e32 v51, v72, v48
	v_mov_b32_e32 v68, v51
	v_mov_b32_e32 v253, v51
	s_nop 1
	v_permlane16_swap_b32_e32 v68, v253
	v_cndmask_b32_e64 v68, v68, v253, s[58:59]
	v_lshl_add_u64 v[48:49], s[10:11], 0, v[70:71]
	v_lshl_add_u64 v[66:67], v[48:49], 0, v[146:147]
	global_store_dwordx4 v[66:67], v[56:59], off
	v_cvt_pk_bf16_f32 v50, v52, v53
	s_waitcnt lgkmcnt(0)
	v_add_f32_e32 v48, v51, v68
	v_mov_b32_e32 v49, v48
	v_mov_b32_e32 v253, v48
	s_nop 1
	v_permlane32_swap_b32_e32 v49, v253
	v_cndmask_b32_e64 v49, v49, v253, s[56:57]
	v_cvt_pk_bf16_f32 v51, v54, v55
	v_cvt_pk_bf16_f32 v52, v62, v63
	v_cvt_pk_bf16_f32 v53, v60, v61
	global_store_dwordx4 v[66:67], v[50:53], off offset:256
	s_and_saveexec_b64 s[20:21], s[2:3]
	s_cbranch_execz .LBB0_944
	v_lshl_add_u64 v[50:51], v[64:65], 2, s[12:13]
	s_waitcnt lgkmcnt(0)
	v_add_f32_e32 v48, v48, v49
	global_atomic_add_f32 v[50:51], v48, off
; __device__ __forceinline__ u32x4 pack8(f32x4 a, f32x4 b) { u32x4 w; w.x = cvt_pk_bf16(a[0], a[1]); w.y = cvt_pk_bf16(a[2], a[3]); w.z = cvt_pk_bf16(b[0], b[1]); w.w = cvt_pk_bf16(b[2], b[3]); return w; }
;     __device__ __forceinline__ void operator()(const f32x4 (&acc)[2][2][4][2], const pg8::Unit& u, int wr, int wc, int fr, int fq) const {
;     ...
;             for (int m = 0; m < 4; ++m) { const int row = u.pm * 256 + ai * 128 + wr * 64 + m * 16 + fr; float ss = 0.f;
; #pragma unroll
;                 for (int bj = 0; bj < 2; ++bj) { const int col = u.pn * 256 + bj * 128 + wc * 32 + 8 * fq;
;                     f32x4 x0, x1; unpack_bf16x8(*(const u32x4*)(X2B + (size_t)row * D + col), x0, x1);
;                     const f32x4 v0 = acc[ai][bj][m][0] + x0, v1 = acc[ai][bj][m][1] + x1;
;                     ss += (v0[0] * v0[0] + v0[1] * v0[1]) + (v0[2] * v0[2] + v0[3] * v0[3]) + (v1[0] * v1[0] + v1[1] * v1[1]) + (v1[2] * v1[2] + v1[3] * v1[3]);
;                     *(u32x4*)(X3B + (size_t)row * D + col) = pack8(v0, v1); }
;                 ss += __shfl_xor(ss, 16); ss += __shfl_xor(ss, 32);
;                 if (fq == 0) atomicAdd(rss + row, ss); }
.LBB0_944:
	s_or_b64 exec, exec, s[20:21]
	v_add_u32_e32 v48, 0x90, v148
	s_waitcnt lgkmcnt(0)
	v_ashrrev_i32_e32 v49, 31, v48
	v_lshlrev_b64 v[54:55], 11, v[48:49]
	v_lshl_add_u64 v[50:51], s[8:9], 0, v[54:55]
	v_lshl_add_u64 v[56:57], v[50:51], 0, v[146:147]
	s_nop 0
	s_waitcnt vmcnt(15)
	v_lshlrev_b32_e32 v58, 16, v210
	v_and_b32_e32 v59, 0xffff0000, v210
	v_lshlrev_b32_e32 v50, 16, v211
	v_and_b32_e32 v51, 0xffff0000, v211
	v_lshlrev_b32_e32 v60, 16, v212
	v_and_b32_e32 v61, 0xffff0000, v212
	v_lshlrev_b32_e32 v52, 16, v213
	v_and_b32_e32 v53, 0xffff0000, v213
	v_pk_add_f32 v[50:51], v[46:47], v[50:51]
	v_pk_add_f32 v[58:59], v[44:45], v[58:59]
	v_pk_add_f32 v[52:53], v[42:43], v[52:53]
	v_pk_add_f32 v[60:61], v[40:41], v[60:61]
	v_cvt_pk_bf16_f32 v40, v58, v59
	v_cvt_pk_bf16_f32 v41, v50, v51
	v_mul_f32_e32 v51, v51, v51
	v_cvt_pk_bf16_f32 v42, v60, v61
	v_cvt_pk_bf16_f32 v43, v52, v53
	s_nop 0
	v_mul_f32_e32 v56, v59, v59
	v_mul_f32_e32 v57, v61, v61
	v_fmac_f32_e32 v56, v58, v58
	v_fmac_f32_e32 v51, v50, v50
	v_mul_f32_e32 v53, v53, v53
	v_fmac_f32_e32 v57, v60, v60
	v_add_f32_e32 v50, v56, v51
	v_fmac_f32_e32 v53, v52, v52
	v_add_f32_e32 v50, v57, v50
	v_add_f32_e32 v56, v53, v50
	s_waitcnt vmcnt(14)
	v_lshlrev_b32_e32 v50, 16, v214
	v_and_b32_e32 v51, 0xffff0000, v214
	v_lshlrev_b32_e32 v44, 16, v215
	v_and_b32_e32 v45, 0xffff0000, v215
	v_lshlrev_b32_e32 v52, 16, v216
	v_and_b32_e32 v53, 0xffff0000, v216
	v_lshlrev_b32_e32 v46, 16, v217
	v_and_b32_e32 v47, 0xffff0000, v217
	v_pk_add_f32 v[38:39], v[38:39], v[44:45]
	v_pk_add_f32 v[36:37], v[36:37], v[50:51]
	v_pk_add_f32 v[44:45], v[34:35], v[46:47]
	v_pk_add_f32 v[46:47], v[32:33], v[52:53]
	v_mul_f32_e32 v32, v37, v37
	v_mul_f32_e32 v33, v39, v39
	v_mul_f32_e32 v34, v47, v47
	v_fmac_f32_e32 v32, v36, v36
	v_fmac_f32_e32 v33, v38, v38
	v_mul_f32_e32 v35, v45, v45
	v_fmac_f32_e32 v34, v46, v46
	v_add_f32_e32 v32, v32, v33
	v_add_f32_e32 v32, v34, v32
	v_fmac_f32_e32 v35, v44, v44
	v_add_f32_e32 v32, v35, v32
	v_add_f32_e32 v35, v56, v32
	v_mov_b32_e32 v52, v35
	v_mov_b32_e32 v253, v35
	s_nop 1
	v_permlane16_swap_b32_e32 v52, v253
	v_cndmask_b32_e64 v52, v52, v253, s[58:59]
	v_lshl_add_u64 v[32:33], s[10:11], 0, v[54:55]
	v_lshl_add_u64 v[50:51], v[32:33], 0, v[146:147]
	global_store_dwordx4 v[50:51], v[40:43], off
	v_cvt_pk_bf16_f32 v34, v36, v37
	s_waitcnt lgkmcnt(0)
	v_add_f32_e32 v32, v35, v52
	v_mov_b32_e32 v33, v32
	v_mov_b32_e32 v253, v32
	s_nop 1
	v_permlane32_swap_b32_e32 v33, v253
	v_cndmask_b32_e64 v33, v33, v253, s[56:57]
	v_cvt_pk_bf16_f32 v35, v38, v39
	v_cvt_pk_bf16_f32 v36, v46, v47
	v_cvt_pk_bf16_f32 v37, v44, v45
	global_store_dwordx4 v[50:51], v[34:37], off offset:256
	s_and_saveexec_b64 s[20:21], s[2:3]
	s_cbranch_execz .LBB0_946
	v_lshl_add_u64 v[34:35], v[48:49], 2, s[12:13]
	s_waitcnt lgkmcnt(0)
	v_add_f32_e32 v32, v32, v33
	global_atomic_add_f32 v[34:35], v32, off
; __device__ __forceinline__ u32x4 pack8(f32x4 a, f32x4 b) { u32x4 w; w.x = cvt_pk_bf16(a[0], a[1]); w.y = cvt_pk_bf16(a[2], a[3]); w.z = cvt_pk_bf16(b[0], b[1]); w.w = cvt_pk_bf16(b[2], b[3]); return w; }
;     __device__ __forceinline__ void operator()(const f32x4 (&acc)[2][2][4][2], const pg8::Unit& u, int wr, int wc, int fr, int fq) const {
;     ...
;             for (int m = 0; m < 4; ++m) { const int row = u.pm * 256 + ai * 128 + wr * 64 + m * 16 + fr; float ss = 0.f;
; #pragma unroll
;                 for (int bj = 0; bj < 2; ++bj) { const int col = u.pn * 256 + bj * 128 + wc * 32 + 8 * fq;
;                     f32x4 x0, x1; unpack_bf16x8(*(const u32x4*)(X2B + (size_t)row * D + col), x0, x1);
;                     const f32x4 v0 = acc[ai][bj][m][0] + x0, v1 = acc[ai][bj][m][1] + x1;
;                     ss += (v0[0] * v0[0] + v0[1] * v0[1]) + (v0[2] * v0[2] + v0[3] * v0[3]) + (v1[0] * v1[0] + v1[1] * v1[1]) + (v1[2] * v1[2] + v1[3] * v1[3]);
;                     *(u32x4*)(X3B + (size_t)row * D + col) = pack8(v0, v1); }
;                 ss += __shfl_xor(ss, 16); ss += __shfl_xor(ss, 32);
;                 if (fq == 0) atomicAdd(rss + row, ss); }
.LBB0_946:
	s_or_b64 exec, exec, s[20:21]
	v_add_u32_e32 v32, 0xa0, v148
	s_waitcnt lgkmcnt(0)
	v_ashrrev_i32_e32 v33, 31, v32
	v_lshlrev_b64 v[38:39], 11, v[32:33]
	v_lshl_add_u64 v[34:35], s[8:9], 0, v[38:39]
	v_lshl_add_u64 v[40:41], v[34:35], 0, v[146:147]
	s_nop 0
	s_waitcnt vmcnt(15)
	v_lshlrev_b32_e32 v42, 16, v218
	v_and_b32_e32 v43, 0xffff0000, v218
	v_lshlrev_b32_e32 v34, 16, v219
	v_and_b32_e32 v35, 0xffff0000, v219
	v_lshlrev_b32_e32 v44, 16, v220
	v_and_b32_e32 v45, 0xffff0000, v220
	v_lshlrev_b32_e32 v36, 16, v221
	v_and_b32_e32 v37, 0xffff0000, v221
	v_pk_add_f32 v[34:35], v[30:31], v[34:35]
	v_pk_add_f32 v[42:43], v[28:29], v[42:43]
	v_pk_add_f32 v[36:37], v[26:27], v[36:37]
	v_pk_add_f32 v[44:45], v[24:25], v[44:45]
	v_cvt_pk_bf16_f32 v24, v42, v43
	v_cvt_pk_bf16_f32 v25, v34, v35
	v_mul_f32_e32 v35, v35, v35
	v_cvt_pk_bf16_f32 v26, v44, v45
	v_cvt_pk_bf16_f32 v27, v36, v37
	s_nop 0
	v_mul_f32_e32 v40, v43, v43
	v_mul_f32_e32 v41, v45, v45
	v_fmac_f32_e32 v40, v42, v42
	v_fmac_f32_e32 v35, v34, v34
	v_mul_f32_e32 v37, v37, v37
	v_fmac_f32_e32 v41, v44, v44
	v_add_f32_e32 v34, v40, v35
	v_fmac_f32_e32 v37, v36, v36
	v_add_f32_e32 v34, v41, v34
	v_add_f32_e32 v40, v37, v34
	s_waitcnt vmcnt(14)
	v_lshlrev_b32_e32 v34, 16, v222
	v_and_b32_e32 v35, 0xffff0000, v222
	v_lshlrev_b32_e32 v28, 16, v223
	v_and_b32_e32 v29, 0xffff0000, v223
	v_lshlrev_b32_e32 v36, 16, v224
	v_and_b32_e32 v37, 0xffff0000, v224
	v_lshlrev_b32_e32 v30, 16, v225
	v_and_b32_e32 v31, 0xffff0000, v225
	v_pk_add_f32 v[22:23], v[22:23], v[28:29]
	v_pk_add_f32 v[20:21], v[20:21], v[34:35]
	v_pk_add_f32 v[28:29], v[18:19], v[30:31]
	v_pk_add_f32 v[30:31], v[16:17], v[36:37]
	v_mul_f32_e32 v16, v21, v21
	v_mul_f32_e32 v17, v23, v23
	v_mul_f32_e32 v18, v31, v31
	v_fmac_f32_e32 v16, v20, v20
	v_fmac_f32_e32 v17, v22, v22
	v_mul_f32_e32 v19, v29, v29
	v_fmac_f32_e32 v18, v30, v30
	v_add_f32_e32 v16, v16, v17
	v_add_f32_e32 v16, v18, v16
	v_fmac_f32_e32 v19, v28, v28
	v_add_f32_e32 v16, v19, v16
	v_add_f32_e32 v19, v40, v16
	v_mov_b32_e32 v36, v19
	v_mov_b32_e32 v253, v19
	s_nop 1
	v_permlane16_swap_b32_e32 v36, v253
	v_cndmask_b32_e64 v36, v36, v253, s[58:59]
	v_lshl_add_u64 v[16:17], s[10:11], 0, v[38:39]
	v_lshl_add_u64 v[34:35], v[16:17], 0, v[146:147]
	global_store_dwordx4 v[34:35], v[24:27], off
	v_cvt_pk_bf16_f32 v18, v20, v21
	s_waitcnt lgkmcnt(0)
	v_add_f32_e32 v16, v19, v36
	v_mov_b32_e32 v17, v16
	v_mov_b32_e32 v253, v16
	s_nop 1
	v_permlane32_swap_b32_e32 v17, v253
	v_cndmask_b32_e64 v17, v17, v253, s[56:57]
	v_cvt_pk_bf16_f32 v19, v22, v23
	v_cvt_pk_bf16_f32 v20, v30, v31
	v_cvt_pk_bf16_f32 v21, v28, v29
	global_store_dwordx4 v[34:35], v[18:21], off offset:256
	s_and_saveexec_b64 s[20:21], s[2:3]
	s_cbranch_execz .LBB0_948
	v_lshl_add_u64 v[18:19], v[32:33], 2, s[12:13]
	s_waitcnt lgkmcnt(0)
	v_add_f32_e32 v16, v16, v17
	global_atomic_add_f32 v[18:19], v16, off
.LBB0_948:
	s_or_b64 exec, exec, s[20:21]
	v_add_u32_e32 v16, 0xb0, v148
	s_waitcnt lgkmcnt(0)
	v_ashrrev_i32_e32 v17, 31, v16
	v_lshlrev_b64 v[22:23], 11, v[16:17]
	v_lshl_add_u64 v[18:19], s[8:9], 0, v[22:23]
	v_lshl_add_u64 v[24:25], v[18:19], 0, v[146:147]
	s_nop 0
	s_waitcnt vmcnt(15)
	v_lshlrev_b32_e32 v26, 16, v234
	v_and_b32_e32 v27, 0xffff0000, v234
	v_lshlrev_b32_e32 v18, 16, v235
	v_and_b32_e32 v19, 0xffff0000, v235
	v_lshlrev_b32_e32 v28, 16, v236
	v_and_b32_e32 v29, 0xffff0000, v236
	v_lshlrev_b32_e32 v20, 16, v237
	v_and_b32_e32 v21, 0xffff0000, v237
	v_pk_add_f32 v[18:19], v[14:15], v[18:19]
	v_pk_add_f32 v[26:27], v[12:13], v[26:27]
	v_pk_add_f32 v[20:21], v[10:11], v[20:21]
	v_pk_add_f32 v[28:29], v[8:9], v[28:29]
	v_cvt_pk_bf16_f32 v8, v26, v27
	v_cvt_pk_bf16_f32 v9, v18, v19
	v_mul_f32_e32 v19, v19, v19
	v_cvt_pk_bf16_f32 v10, v28, v29
	v_cvt_pk_bf16_f32 v11, v20, v21
	s_nop 0
	v_mul_f32_e32 v24, v27, v27
	v_mul_f32_e32 v25, v29, v29
	v_fmac_f32_e32 v24, v26, v26
	v_fmac_f32_e32 v19, v18, v18
	v_mul_f32_e32 v21, v21, v21
	v_fmac_f32_e32 v25, v28, v28
	v_add_f32_e32 v18, v24, v19
	v_fmac_f32_e32 v21, v20, v20
	v_add_f32_e32 v18, v25, v18
	v_add_f32_e32 v24, v21, v18
	s_waitcnt vmcnt(14)
	v_lshlrev_b32_e32 v18, 16, v238
	v_and_b32_e32 v19, 0xffff0000, v238
	v_lshlrev_b32_e32 v12, 16, v239
	v_and_b32_e32 v13, 0xffff0000, v239
	v_lshlrev_b32_e32 v20, 16, v240
	v_and_b32_e32 v21, 0xffff0000, v240
	v_lshlrev_b32_e32 v14, 16, v241
	v_and_b32_e32 v15, 0xffff0000, v241
	v_pk_add_f32 v[6:7], v[6:7], v[12:13]
	v_pk_add_f32 v[4:5], v[4:5], v[18:19]
	v_pk_add_f32 v[12:13], v[2:3], v[14:15]
	v_pk_add_f32 v[14:15], v[0:1], v[20:21]
	v_mul_f32_e32 v0, v5, v5
	v_mul_f32_e32 v1, v7, v7
	v_mul_f32_e32 v2, v15, v15
	v_fmac_f32_e32 v0, v4, v4
	v_fmac_f32_e32 v1, v6, v6
	v_mul_f32_e32 v3, v13, v13
	v_fmac_f32_e32 v2, v14, v14
	v_add_f32_e32 v0, v0, v1
	v_add_f32_e32 v0, v2, v0
	v_fmac_f32_e32 v3, v12, v12
	v_add_f32_e32 v0, v3, v0
	v_add_f32_e32 v3, v24, v0
	v_mov_b32_e32 v20, v3
	v_mov_b32_e32 v253, v3
	s_nop 1
	v_permlane16_swap_b32_e32 v20, v253
	v_cndmask_b32_e64 v20, v20, v253, s[58:59]
	v_lshl_add_u64 v[0:1], s[10:11], 0, v[22:23]
	v_lshl_add_u64 v[18:19], v[0:1], 0, v[146:147]
	global_store_dwordx4 v[18:19], v[8:11], off
	v_cvt_pk_bf16_f32 v2, v4, v5
	s_waitcnt lgkmcnt(0)
	v_add_f32_e32 v0, v3, v20
	v_mov_b32_e32 v1, v0
	v_mov_b32_e32 v253, v0
	s_nop 1
	v_permlane32_swap_b32_e32 v1, v253
	v_cndmask_b32_e64 v1, v1, v253, s[56:57]
	v_cvt_pk_bf16_f32 v3, v6, v7
	v_cvt_pk_bf16_f32 v4, v14, v15
	v_cvt_pk_bf16_f32 v5, v12, v13
	global_store_dwordx4 v[18:19], v[2:5], off offset:256
	s_and_saveexec_b64 s[20:21], s[2:3]
	s_cbranch_execz .LBB0_950
	v_lshl_add_u64 v[2:3], v[16:17], 2, s[12:13]
	s_waitcnt lgkmcnt(0)
	v_add_f32_e32 v0, v0, v1
	global_atomic_add_f32 v[2:3], v0, off
